# norm phases 3 and 10: lane-pair exchange gives 16-byte write-through stores, L2 write-back walk only after phases 0 and 5
# baseline (speedup 1.0000x reference)
.LBB0_129:
	s_or_b64 exec, exec, s[2:3]
	s_waitcnt lgkmcnt(0)
	v_pk_mul_f32 v[56:57], v[30:31], v[30:31]
	v_pk_mul_f32 v[62:63], v[36:37], v[36:37]
	v_pk_mul_f32 v[60:61], v[26:27], v[26:27]
	global_load_dwordx4 v[48:51], v[6:7], off
	global_load_dwordx4 v[52:55], v[6:7], off offset:1024
	v_pk_mul_f32 v[72:73], v[34:35], v[34:35]
	v_mov_b32_e32 v74, v56
	v_mov_b32_e32 v75, v62
	v_mov_b32_e32 v62, v57
	global_load_dwordx4 v[56:59], v[6:7], off offset:2048
	v_pk_add_f32 v[62:63], v[74:75], v[62:63]
	v_mov_b32_e32 v74, v60
	v_mov_b32_e32 v75, v72
	v_pk_add_f32 v[74:75], v[74:75], v[62:63]
	v_mov_b32_e32 v72, v61
	global_load_dwordx4 v[60:63], v[6:7], off offset:3072
	v_pk_mul_f32 v[68:69], v[32:33], v[32:33]
	v_pk_mul_f32 v[70:71], v[40:41], v[40:41]
	v_pk_mul_f32 v[64:65], v[28:29], v[28:29]
	v_pk_mul_f32 v[66:67], v[38:39], v[38:39]
	v_pk_add_f32 v[72:73], v[72:73], v[74:75]
	v_mov_b32_e32 v74, v68
	v_mov_b32_e32 v75, v70
	v_mov_b32_e32 v70, v69
	v_pk_add_f32 v[68:69], v[74:75], v[70:71]
	v_mov_b32_e32 v70, v64
	v_mov_b32_e32 v71, v66
	v_pk_add_f32 v[68:69], v[70:71], v[68:69]
	v_mov_b32_e32 v66, v65
	v_pk_add_f32 v[64:65], v[66:67], v[68:69]
	v_add_f32_e32 v0, v72, v73
	v_add_f32_e32 v0, v65, v0
	v_add_f32_e32 v0, v64, v0
	ds_bpermute_b32 v3, v17, v0
	s_mov_b32 s22, 0x800000
	s_waitcnt vmcnt(7)
	v_lshlrev_b32_e32 v64, 16, v24
	v_and_b32_e32 v65, 0xffff0000, v24
	v_lshlrev_b32_e32 v24, 16, v25
	s_waitcnt lgkmcnt(0)
	v_add_f32_e32 v0, v0, v3
	ds_bpermute_b32 v3, v42, v0
	v_and_b32_e32 v25, 0xffff0000, v25
	s_waitcnt vmcnt(6)
	v_lshlrev_b32_e32 v66, 16, v22
	v_and_b32_e32 v67, 0xffff0000, v22
	s_waitcnt vmcnt(5)
	v_lshlrev_b32_e32 v68, 16, v20
	s_waitcnt lgkmcnt(0)
	v_add_f32_e32 v0, v0, v3
	ds_bpermute_b32 v3, v43, v0
	v_and_b32_e32 v69, 0xffff0000, v20
	v_lshlrev_b32_e32 v20, 16, v21
	v_and_b32_e32 v21, 0xffff0000, v21
	v_lshlrev_b32_e32 v22, 16, v23
	s_waitcnt lgkmcnt(0)
	v_add_f32_e32 v0, v0, v3
	ds_bpermute_b32 v3, v44, v0
	v_and_b32_e32 v23, 0xffff0000, v23
	s_waitcnt vmcnt(4)
	v_lshlrev_b32_e32 v70, 16, v18
	v_and_b32_e32 v71, 0xffff0000, v18
	v_lshlrev_b32_e32 v18, 16, v19
	s_waitcnt lgkmcnt(0)
	v_add_f32_e32 v0, v0, v3
	ds_bpermute_b32 v3, v45, v0
	v_and_b32_e32 v19, 0xffff0000, v19
	s_mov_b64 s[2:3], 0xc300000
	s_waitcnt lgkmcnt(0)
	v_add_f32_e32 v0, v0, v3
	ds_bpermute_b32 v3, v46, v0
	s_waitcnt lgkmcnt(0)
	v_add_f32_e32 v0, v0, v3
	v_fmamk_f32 v0, v0, 0x3a800000, v161
	v_mul_f32_e32 v3, 0x4b800000, v0
	v_cmp_gt_f32_e32 vcc, s22, v0
	s_nop 1
	v_cndmask_b32_e32 v0, v0, v3, vcc
	v_rsq_f32_e32 v0, v0
	s_nop 0
	v_mul_f32_e32 v3, 0x45800000, v0
	v_cndmask_b32_e32 v0, v0, v3, vcc
	v_pk_mul_f32 v[26:27], v[26:27], v[0:1] op_sel_hi:[1,0]
	v_pk_mul_f32 v[30:31], v[30:31], v[0:1] op_sel_hi:[1,0]
	v_pk_mul_f32 v[36:37], v[36:37], v[0:1] op_sel_hi:[1,0]
	v_pk_mul_f32 v[38:39], v[38:39], v[0:1] op_sel_hi:[1,0]
	s_waitcnt vmcnt(3)
	v_pk_mul_f32 v[30:31], v[48:49], v[30:31]
	v_pk_mul_f32 v[26:27], v[50:51], v[26:27]
	s_waitcnt vmcnt(2)
	v_pk_mul_f32 v[36:37], v[52:53], v[36:37]
	v_pk_mul_f32 v[34:35], v[34:35], v[0:1] op_sel_hi:[1,0]
	v_pk_fma_f32 v[24:25], v[16:17], v[24:25], v[26:27] op_sel_hi:[0,1,1]
	v_pk_fma_f32 v[26:27], v[16:17], v[64:65], v[30:31] op_sel_hi:[0,1,1]
	v_pk_fma_f32 v[30:31], v[16:17], v[66:67], v[36:37] op_sel_hi:[0,1,1]
	s_waitcnt vmcnt(1)
	v_pk_mul_f32 v[36:37], v[58:59], v[38:39]
	v_pk_mul_f32 v[28:29], v[28:29], v[0:1] op_sel_hi:[1,0]
	v_pk_mul_f32 v[32:33], v[32:33], v[0:1] op_sel_hi:[1,0]
	v_pk_mul_f32 v[40:41], v[40:41], v[0:1] op_sel_hi:[1,0]
	v_pk_mul_f32 v[34:35], v[54:55], v[34:35]
	v_pk_fma_f32 v[20:21], v[16:17], v[20:21], v[36:37] op_sel_hi:[0,1,1]
	s_waitcnt vmcnt(0)
	v_pk_mul_f32 v[32:33], v[60:61], v[32:33]
	v_pk_mul_f32 v[28:29], v[62:63], v[28:29]
	v_mov_b32_e32 v36, v27
	v_mov_b32_e32 v37, v31
	v_pk_fma_f32 v[22:23], v[16:17], v[22:23], v[34:35] op_sel_hi:[0,1,1]
	v_pk_mul_f32 v[34:35], v[56:57], v[40:41]
	v_pk_fma_f32 v[18:19], v[16:17], v[18:19], v[28:29] op_sel_hi:[0,1,1]
	v_pk_fma_f32 v[28:29], v[16:17], v[70:71], v[32:33] op_sel_hi:[0,1,1]
	v_mov_b32_e32 v32, v26
	v_mov_b32_e32 v33, v30
	v_pk_mul_f32 v[36:37], v[36:37], v[36:37]
	v_pk_fma_f32 v[34:35], v[16:17], v[68:69], v[34:35] op_sel_hi:[0,1,1]
	v_pk_fma_f32 v[32:33], v[32:33], v[32:33], v[36:37]
	v_mov_b32_e32 v36, v24
	v_mov_b32_e32 v37, v22
	v_pk_fma_f32 v[32:33], v[36:37], v[36:37], v[32:33]
	v_mov_b32_e32 v36, v25
	v_mov_b32_e32 v37, v23
	v_mov_b32_e32 v38, v29
	v_mov_b32_e32 v39, v35
	v_pk_fma_f32 v[32:33], v[36:37], v[36:37], v[32:33]
	v_mov_b32_e32 v36, v28
	v_mov_b32_e32 v37, v34
	v_pk_mul_f32 v[38:39], v[38:39], v[38:39]
	v_add_f32_e32 v0, v32, v33
	v_pk_fma_f32 v[36:37], v[36:37], v[36:37], v[38:39]
	v_mov_b32_e32 v38, v18
	v_mov_b32_e32 v39, v20
	v_pk_fma_f32 v[36:37], v[38:39], v[38:39], v[36:37]
	v_mov_b32_e32 v38, v19
	v_mov_b32_e32 v39, v21
	v_pk_fma_f32 v[36:37], v[38:39], v[38:39], v[36:37]
	v_lshl_add_u64 v[32:33], v[14:15], 0, s[2:3]
	v_add_f32_e32 v0, v37, v0
	v_add_f32_e32 v0, v36, v0
	ds_bpermute_b32 v3, v17, v0
	s_mov_b64 s[2:3], 0xc300200
	v_lshl_add_u64 v[36:37], v[14:15], 0, s[2:3]
	s_mov_b64 s[2:3], 0xc300400
	v_lshl_add_u64 v[38:39], v[14:15], 0, s[2:3]
	s_waitcnt lgkmcnt(0)
	v_add_f32_e32 v0, v0, v3
	ds_bpermute_b32 v3, v42, v0
	s_mov_b64 s[2:3], 0xc300600
	v_lshl_add_u64 v[14:15], v[14:15], 0, s[2:3]
	s_waitcnt lgkmcnt(0)
	v_add_f32_e32 v0, v0, v3
	ds_bpermute_b32 v3, v43, v0
	s_waitcnt lgkmcnt(0)
	v_add_f32_e32 v0, v0, v3
	ds_bpermute_b32 v3, v44, v0
	s_waitcnt lgkmcnt(0)
	v_add_f32_e32 v0, v0, v3
	ds_bpermute_b32 v3, v45, v0
	s_waitcnt lgkmcnt(0)
	v_add_f32_e32 v0, v0, v3
	ds_bpermute_b32 v3, v46, v0
	s_waitcnt lgkmcnt(0)
	v_add_f32_e32 v0, v0, v3
	v_fmamk_f32 v3, v0, 0x3a800000, v161
	v_mul_f32_e32 v0, 0x4b800000, v3
	v_cmp_gt_f32_e32 vcc, s22, v3
	s_nop 1
	v_cndmask_b32_e32 v0, v3, v0, vcc
	v_rsq_f32_e32 v0, v0
	s_nop 0
	v_mul_f32_e32 v16, 0x45800000, v0
	v_cndmask_b32_e32 v0, v0, v16, vcc
	v_pk_mul_f32 v[24:25], v[24:25], v[0:1] op_sel_hi:[1,0]
	v_pk_mul_f32 v[26:27], v[26:27], v[0:1] op_sel_hi:[1,0]
	v_pk_mul_f32 v[22:23], v[22:23], v[0:1] op_sel_hi:[1,0]
	v_cvt_pk_bf16_f32 v26, v26, v27
	v_cvt_pk_bf16_f32 v27, v24, v25
	v_pk_mul_f32 v[24:25], v[30:31], v[0:1] op_sel_hi:[1,0]
	v_cvt_pk_bf16_f32 v24, v24, v25
	v_cvt_pk_bf16_f32 v25, v22, v23
	v_pk_mul_f32 v[20:21], v[20:21], v[0:1] op_sel_hi:[1,0]
	v_pk_mul_f32 v[22:23], v[34:35], v[0:1] op_sel_hi:[1,0]
	v_cvt_pk_bf16_f32 v22, v22, v23
	v_cvt_pk_bf16_f32 v23, v20, v21
	v_pk_mul_f32 v[20:21], v[28:29], v[0:1] op_sel_hi:[1,0]
	v_pk_mul_f32 v[18:19], v[18:19], v[0:1] op_sel_hi:[1,0]
	v_cvt_pk_bf16_f32 v20, v20, v21
	s_nop 0
	v_cvt_pk_bf16_f32 v21, v18, v19
	s_mov_b32 s2, 0xaaaaaaaa
	s_mov_b32 s3, 0xaaaaaaaa
	v_cndmask_b32_e64 v118, v24, v26, s[2:3]
	v_cndmask_b32_e64 v119, v25, v27, s[2:3]
	v_cndmask_b32_e64 v132, v20, v22, s[2:3]
	v_cndmask_b32_e64 v133, v21, v23, s[2:3]
	v_mov_b32_e32 v130, 0x1f8
	v_cndmask_b32_e64 v130, 0, v130, s[2:3]
	v_add_u32_e32 v130, v32, v130
	v_mov_b32_e32 v131, v33
	v_mov_b32_dpp v128, v118 quad_perm:[1,0,3,2] row_mask:0xf bank_mask:0xf
	v_mov_b32_dpp v129, v119 quad_perm:[1,0,3,2] row_mask:0xf bank_mask:0xf
	s_nop 1
	v_cndmask_b32_e64 v120, v26, v128, s[2:3]
	v_cndmask_b32_e64 v121, v27, v129, s[2:3]
	v_cndmask_b32_e64 v122, v128, v24, s[2:3]
	v_cndmask_b32_e64 v123, v129, v25, s[2:3]
	global_store_dwordx4 v[130:131], v[120:123], off sc1
	v_mov_b32_dpp v118, v132 quad_perm:[1,0,3,2] row_mask:0xf bank_mask:0xf
	v_mov_b32_dpp v119, v133 quad_perm:[1,0,3,2] row_mask:0xf bank_mask:0xf
	s_nop 1
	v_cndmask_b32_e64 v124, v22, v118, s[2:3]
	v_cndmask_b32_e64 v125, v23, v119, s[2:3]
	v_cndmask_b32_e64 v126, v118, v20, s[2:3]
	v_cndmask_b32_e64 v127, v119, v21, s[2:3]
	global_store_dwordx4 v[130:131], v[124:127], off offset:1024 sc1
	s_and_saveexec_b64 s[2:3], s[0:1]
	s_cbranch_execz .LBB0_124
	v_mul_f32_e32 v0, v3, v0
	global_store_dword v[12:13], v0, off sc1
	s_branch .LBB0_124

.LBB0_278:
	s_or_b64 exec, exec, s[0:1]
	v_pk_mul_f32 v[64:65], v[32:33], v[32:33]
	v_pk_mul_f32 v[66:67], v[28:29], v[28:29]
	v_pk_mul_f32 v[60:61], v[34:35], v[34:35]
	v_pk_mul_f32 v[62:63], v[30:31], v[30:31]
	v_mov_b32_e32 v68, v64
	v_mov_b32_e32 v69, v66
	v_mov_b32_e32 v66, v65
	v_pk_add_f32 v[64:65], v[68:69], v[66:67]
	v_mov_b32_e32 v66, v60
	v_mov_b32_e32 v67, v62
	v_pk_mul_f32 v[56:57], v[2:3], v[2:3]
	v_pk_mul_f32 v[58:59], v[24:25], v[24:25]
	v_pk_add_f32 v[64:65], v[66:67], v[64:65]
	v_mov_b32_e32 v62, v61
	v_pk_mul_f32 v[52:53], v[4:5], v[4:5]
	v_pk_mul_f32 v[54:55], v[26:27], v[26:27]
	v_pk_add_f32 v[60:61], v[62:63], v[64:65]
	v_mov_b32_e32 v62, v56
	v_mov_b32_e32 v63, v58
	v_mov_b32_e32 v58, v57
	v_pk_add_f32 v[56:57], v[62:63], v[58:59]
	v_mov_b32_e32 v58, v52
	v_mov_b32_e32 v59, v54
	v_pk_add_f32 v[56:57], v[58:59], v[56:57]
	v_mov_b32_e32 v54, v53
	v_pk_add_f32 v[52:53], v[54:55], v[56:57]
	v_add_f32_e32 v7, v60, v61
	v_add_f32_e32 v7, v53, v7
	v_add_f32_e32 v7, v52, v7
	ds_bpermute_b32 v52, v23, v7
	s_mov_b32 s2, 0x800000
	s_waitcnt vmcnt(3)
	v_lshlrev_b32_e32 v48, 16, v42
	v_and_b32_e32 v49, 0xffff0000, v42
	v_lshlrev_b32_e32 v50, 16, v43
	s_waitcnt lgkmcnt(0)
	v_add_f32_e32 v7, v7, v52
	ds_bpermute_b32 v52, v80, v7
	v_and_b32_e32 v51, 0xffff0000, v43
	s_waitcnt vmcnt(2)
	v_lshlrev_b32_e32 v44, 16, v40
	v_and_b32_e32 v45, 0xffff0000, v40
	v_lshlrev_b32_e32 v46, 16, v41
	s_waitcnt lgkmcnt(0)
	v_add_f32_e32 v7, v7, v52
	ds_bpermute_b32 v52, v81, v7
	v_and_b32_e32 v47, 0xffff0000, v41
	s_waitcnt vmcnt(1)
	v_lshlrev_b32_e32 v40, 16, v38
	v_and_b32_e32 v41, 0xffff0000, v38
	v_lshlrev_b32_e32 v42, 16, v39
	s_waitcnt lgkmcnt(0)
	v_add_f32_e32 v7, v7, v52
	ds_bpermute_b32 v52, v82, v7
	v_and_b32_e32 v43, 0xffff0000, v39
	s_waitcnt vmcnt(0)
	v_lshlrev_b32_e32 v38, 16, v36
	v_and_b32_e32 v39, 0xffff0000, v36
	v_lshlrev_b32_e32 v36, 16, v37
	s_waitcnt lgkmcnt(0)
	v_add_f32_e32 v7, v7, v52
	ds_bpermute_b32 v52, v83, v7
	v_and_b32_e32 v37, 0xffff0000, v37
	s_waitcnt lgkmcnt(0)
	v_add_f32_e32 v7, v7, v52
	ds_bpermute_b32 v52, v84, v7
	s_waitcnt lgkmcnt(0)
	v_add_f32_e32 v7, v7, v52
	v_fmamk_f32 v7, v7, 0x3a800000, v161
	v_cmp_gt_f32_e64 s[0:1], s2, v7
	v_mul_f32_e32 v52, 0x4b800000, v7
	s_nop 0
	v_cndmask_b32_e64 v7, v7, v52, s[0:1]
	v_rsq_f32_e32 v7, v7
	s_nop 0
	v_mul_f32_e32 v52, 0x45800000, v7
	v_cndmask_b32_e64 v7, v7, v52, s[0:1]
	v_mul_f32_e32 v52, 0.5, v7
	v_pk_mul_f32 v[54:55], v[34:35], v[52:53] op_sel_hi:[1,0]
	v_pk_mul_f32 v[56:57], v[32:33], v[52:53] op_sel_hi:[1,0]
	global_load_dwordx4 v[32:35], v[14:15], off
	s_waitcnt vmcnt(0)
	v_pk_mul_f32 v[56:57], v[32:33], v[56:57]
	v_pk_mul_f32 v[32:33], v[34:35], v[54:55]
	v_pk_fma_f32 v[34:35], v[22:23], v[48:49], v[56:57] op_sel_hi:[0,1,1]
	v_pk_fma_f32 v[32:33], v[22:23], v[50:51], v[32:33] op_sel_hi:[0,1,1]
	v_pk_mul_f32 v[48:49], v[30:31], v[52:53] op_sel_hi:[1,0]
	v_pk_mul_f32 v[50:51], v[28:29], v[52:53] op_sel_hi:[1,0]
	global_load_dwordx4 v[28:31], v[14:15], off offset:1024
	s_waitcnt vmcnt(0)
	v_pk_mul_f32 v[50:51], v[28:29], v[50:51]
	v_pk_mul_f32 v[28:29], v[30:31], v[48:49]
	v_pk_fma_f32 v[30:31], v[22:23], v[44:45], v[50:51] op_sel_hi:[0,1,1]
	v_pk_fma_f32 v[28:29], v[22:23], v[46:47], v[28:29] op_sel_hi:[0,1,1]
	v_pk_mul_f32 v[44:45], v[26:27], v[52:53] op_sel_hi:[1,0]
	v_pk_mul_f32 v[46:47], v[24:25], v[52:53] op_sel_hi:[1,0]
	global_load_dwordx4 v[24:27], v[14:15], off offset:2048
	s_waitcnt vmcnt(0)
	v_pk_mul_f32 v[46:47], v[24:25], v[46:47]
	v_pk_mul_f32 v[24:25], v[26:27], v[44:45]
	v_pk_fma_f32 v[26:27], v[22:23], v[40:41], v[46:47] op_sel_hi:[0,1,1]
	v_pk_fma_f32 v[24:25], v[22:23], v[42:43], v[24:25] op_sel_hi:[0,1,1]
	v_pk_mul_f32 v[40:41], v[4:5], v[52:53] op_sel_hi:[1,0]
	v_pk_mul_f32 v[42:43], v[2:3], v[52:53] op_sel_hi:[1,0]
	global_load_dwordx4 v[2:5], v[14:15], off offset:3072
	s_waitcnt vmcnt(0)
	v_pk_mul_f32 v[2:3], v[2:3], v[42:43]
	v_pk_mul_f32 v[4:5], v[4:5], v[40:41]
	v_mov_b32_e32 v41, v27
	v_pk_fma_f32 v[4:5], v[22:23], v[36:37], v[4:5] op_sel_hi:[0,1,1]
	v_pk_fma_f32 v[36:37], v[22:23], v[38:39], v[2:3] op_sel_hi:[0,1,1]
	v_mov_b32_e32 v38, v35
	v_mov_b32_e32 v39, v31
	v_mov_b32_e32 v2, v34
	v_mov_b32_e32 v3, v30
	v_pk_mul_f32 v[38:39], v[38:39], v[38:39]
	v_mov_b32_e32 v40, v37
	v_pk_fma_f32 v[2:3], v[2:3], v[2:3], v[38:39]
	v_mov_b32_e32 v38, v32
	v_mov_b32_e32 v39, v28
	v_pk_fma_f32 v[2:3], v[38:39], v[38:39], v[2:3]
	v_mov_b32_e32 v38, v33
	v_mov_b32_e32 v39, v29
	v_pk_fma_f32 v[2:3], v[38:39], v[38:39], v[2:3]
	v_mov_b32_e32 v38, v36
	v_mov_b32_e32 v39, v26
	v_pk_mul_f32 v[40:41], v[40:41], v[40:41]
	v_add_f32_e32 v2, v2, v3
	v_pk_fma_f32 v[38:39], v[38:39], v[38:39], v[40:41]
	v_mov_b32_e32 v40, v4
	v_mov_b32_e32 v41, v24
	v_pk_fma_f32 v[38:39], v[40:41], v[40:41], v[38:39]
	v_mov_b32_e32 v40, v5
	v_mov_b32_e32 v41, v25
	v_pk_fma_f32 v[38:39], v[40:41], v[40:41], v[38:39]
	s_nop 0
	v_add_f32_e32 v2, v39, v2
	v_add_f32_e32 v2, v38, v2
	ds_bpermute_b32 v3, v23, v2
	s_waitcnt lgkmcnt(0)
	v_add_f32_e32 v2, v2, v3
	ds_bpermute_b32 v3, v80, v2
	s_waitcnt lgkmcnt(0)
	v_add_f32_e32 v2, v2, v3
	ds_bpermute_b32 v3, v81, v2
	s_waitcnt lgkmcnt(0)
	v_add_f32_e32 v2, v2, v3
	ds_bpermute_b32 v3, v82, v2
	s_waitcnt lgkmcnt(0)
	v_add_f32_e32 v2, v2, v3
	ds_bpermute_b32 v3, v83, v2
	s_waitcnt lgkmcnt(0)
	v_add_f32_e32 v2, v2, v3
	ds_bpermute_b32 v3, v84, v2
	s_waitcnt lgkmcnt(0)
	v_add_f32_e32 v2, v2, v3
	v_fmamk_f32 v3, v2, 0x3a800000, v161
	v_cmp_gt_f32_e64 s[0:1], s2, v3
	v_mul_f32_e32 v2, 0x4b800000, v3
	s_nop 0
	v_cndmask_b32_e64 v2, v3, v2, s[0:1]
	v_rsq_f32_e32 v2, v2
	s_nop 0
	v_mul_f32_e32 v7, 0x45800000, v2
	v_cndmask_b32_e64 v2, v2, v7, s[0:1]
	v_pk_mul_f32 v[34:35], v[34:35], v[2:3] op_sel_hi:[1,0]
	v_pk_mul_f32 v[30:31], v[30:31], v[2:3] op_sel_hi:[1,0]
	v_pk_mul_f32 v[24:25], v[24:25], v[2:3] op_sel_hi:[1,0]
	v_pk_mul_f32 v[26:27], v[26:27], v[2:3] op_sel_hi:[1,0]
	v_pk_mul_f32 v[32:33], v[32:33], v[2:3] op_sel_hi:[1,0]
	v_cvt_pk_bf16_f32 v34, v34, v35
	v_pk_mul_f32 v[28:29], v[28:29], v[2:3] op_sel_hi:[1,0]
	v_cvt_pk_bf16_f32 v35, v32, v33
	v_cvt_pk_bf16_f32 v30, v30, v31
	v_cvt_pk_bf16_f32 v31, v28, v29
	v_cvt_pk_bf16_f32 v26, v26, v27
	v_cvt_pk_bf16_f32 v27, v24, v25
	v_pk_mul_f32 v[24:25], v[36:37], v[2:3] op_sel_hi:[1,0]
	v_pk_mul_f32 v[4:5], v[4:5], v[2:3] op_sel_hi:[1,0]
	v_cvt_pk_bf16_f32 v24, v24, v25
	s_nop 0
	v_cvt_pk_bf16_f32 v25, v4, v5
	s_mov_b32 s0, 0xaaaaaaaa
	s_mov_b32 s1, 0xaaaaaaaa
	v_cndmask_b32_e64 v118, v30, v34, s[0:1]
	v_cndmask_b32_e64 v119, v31, v35, s[0:1]
	v_cndmask_b32_e64 v132, v24, v26, s[0:1]
	v_cndmask_b32_e64 v133, v25, v27, s[0:1]
	v_mov_b32_e32 v130, 0x1f8
	v_cndmask_b32_e64 v130, 0, v130, s[0:1]
	v_add_u32_e32 v130, v20, v130
	v_mov_b32_e32 v131, v21
	v_mov_b32_dpp v128, v118 quad_perm:[1,0,3,2] row_mask:0xf bank_mask:0xf
	v_mov_b32_dpp v129, v119 quad_perm:[1,0,3,2] row_mask:0xf bank_mask:0xf
	s_nop 1
	v_cndmask_b32_e64 v120, v34, v128, s[0:1]
	v_cndmask_b32_e64 v121, v35, v129, s[0:1]
	v_cndmask_b32_e64 v122, v128, v30, s[0:1]
	v_cndmask_b32_e64 v123, v129, v31, s[0:1]
	global_store_dwordx4 v[130:131], v[120:123], off sc1
	v_mov_b32_dpp v118, v132 quad_perm:[1,0,3,2] row_mask:0xf bank_mask:0xf
	v_mov_b32_dpp v119, v133 quad_perm:[1,0,3,2] row_mask:0xf bank_mask:0xf
	s_nop 1
	v_cndmask_b32_e64 v124, v26, v118, s[0:1]
	v_cndmask_b32_e64 v125, v27, v119, s[0:1]
	v_cndmask_b32_e64 v126, v118, v24, s[0:1]
	v_cndmask_b32_e64 v127, v119, v25, s[0:1]
	global_store_dwordx4 v[130:131], v[124:127], off offset:1024 sc1
	s_and_saveexec_b64 s[0:1], vcc
	s_cbranch_execz .LBB0_271
	v_mul_f32_e32 v2, v3, v2
	global_store_dword v[18:19], v2, off sc1
	s_branch .LBB0_271

.LBB0_524:
	s_or_b64 exec, exec, s[2:3]
	v_cvt_f32_u32_e32 v5, v3
	s_waitcnt vmcnt(0)
	v_readfirstlane_b32 s2, v4
	v_sub_u32_e32 v4, 0, v3
	v_rcp_iflag_f32_e32 v5, v5
	v_add_u32_e32 v6, s2, v0
	v_mul_f32_e32 v5, 0x4f7ffffe, v5
	v_cvt_u32_f32_e32 v5, v5
	v_mul_lo_u32 v0, v4, v5
	v_mul_hi_u32 v0, v5, v0
	v_add_u32_e32 v0, v5, v0
	v_mul_hi_u32 v0, v6, v0
	v_mul_lo_u32 v4, v0, v3
	v_sub_u32_e32 v4, v6, v4
	v_add_u32_e32 v5, 1, v0
	v_cmp_ge_u32_e32 vcc, v4, v3
	s_nop 1
	v_cndmask_b32_e32 v0, v0, v5, vcc
	v_sub_u32_e32 v5, v4, v3
	v_cndmask_b32_e32 v4, v4, v5, vcc
	v_add_u32_e32 v5, 1, v0
	v_cmp_ge_u32_e32 vcc, v4, v3
	v_add_u32_e32 v4, 1, v6
	s_nop 0
	v_cndmask_b32_e32 v0, v0, v5, vcc
	v_mul_lo_u32 v5, v3, v0
	v_add_u32_e32 v3, v5, v3
	v_cmp_ne_u32_e32 vcc, v4, v3
	s_cbranch_vccnz .Lxb_poll
	s_cmp_eq_u32 s41, 1
	s_cbranch_scc1 .Lxb_wb
	s_cmp_eq_u32 s41, 11
	s_cbranch_scc0 .Lxb_nowb
